# SGU-prep row norms: the 16 independent 6-step wave reductions interleaved (6 LDS round trips instead of 96)
# speedup vs baseline: 1.0093x; 1.0062x over previous
; __device__ __forceinline__ unsigned cvt_pk_bf16(float lo, float hi) { unsigned r; asm volatile("v_cvt_pk_bf16_f32 %0, %1, %2" : "=v"(r) : "v"(lo), "v"(hi)); return r; }
; __device__ __forceinline__ void UNPACK8(const u32x4 q, float (&f)[8]) { f[0] = bflo(q.x); f[1] = bfhi(q.x); f[2] = bflo(q.y); f[3] = bfhi(q.y); f[4] = bflo(q.z); f[5] = bfhi(q.z); f[6] = bflo(q.w); f[7] = bfhi(q.w); }
; __device__ __forceinline__ void pool_chunk(PCP p, int chunk, int tid) {
;     ...
;             const int cnt = (pos + 1 < w) ? pos + 1 : w; const float inv = 1.0f / (float)cnt;
;             u32x4 o; o.x = cvt_pk_bf16(s[0] * inv - z[0], s[1] * inv - z[1]); o.y = cvt_pk_bf16(s[2] * inv - z[2], s[3] * inv - z[3]); o.z = cvt_pk_bf16(s[4] * inv - z[4], s[5] * inv - z[5]); o.w = cvt_pk_bf16(s[6] * inv - z[6], s[7] * inv - z[7]);
;             *(u32x4*)(pooled + (size_t)t * 512 + c) = o;
;             if (pos + 1 >= w) { const u32x4 ow = *(const u32x4*)(proj + (size_t)(t + 1 - w) * 1536 + c); float q[8]; UNPACK8(ow, q);
; #pragma unroll
;                 for (int e = 0; e < 8; ++e) s[e] -= q[e]; } }
; __device__ __forceinline__ void sguprep_chunk(PCP p, int j, LAS unsigned char* lds, int it, int tid) {
;     ...
;         for (int s0 = 0; s0 < 16; ++s0) { const int s = wid * 16 + s0; const u32x4 vw = *(const u32x4*)(proj + (T0 + s) * 1536 + 1024 + lane * 8); float v[8]; UNPACK8(vw, v); float ss = 0.f;
; #pragma unroll
;             for (int e = 0; e < 8; ++e) ss += v[e] * v[e];
;             ss = wave_sum(ss); if (lane == 0) rstd[s] = rsqrtf(ss * (1.0f / 512.0f) + EPS); }
.LBB0_372:
	s_or_b64 exec, exec, s[4:5]
	v_or_b32_e32 v56, 15, v76
	v_mad_i64_i32 v[0:1], s[4:5], v56, s45, v[8:9]
	v_mov_b32_e32 v0, v230
	v_mov_b32_e32 v1, v231
	v_mov_b32_e32 v2, v232
	v_mov_b32_e32 v3, v233
	v_ashrrev_i32_e32 v57, 31, v56
	s_ashr_i32 s3, s2, 31
	s_lshl_b64 s[4:5], s[2:3], 7
	v_lshlrev_b32_e32 v58, 16, v0
	v_and_b32_e32 v0, 0xffff0000, v0
	v_lshlrev_b32_e32 v59, 16, v1
	v_and_b32_e32 v1, 0xffff0000, v1
	v_add_f32_e32 v4, v4, v58
	v_add_f32_e32 v5, v5, v0
	v_lshlrev_b32_e32 v60, 16, v2
	v_and_b32_e32 v2, 0xffff0000, v2
	v_add_f32_e32 v6, v6, v59
	v_add_f32_e32 v7, v7, v1
	v_fma_f32 v4, v68, v4, -v58
	v_fma_f32 v0, v68, v5, -v0
	v_lshlrev_b32_e32 v61, 16, v3
	v_and_b32_e32 v3, 0xffff0000, v3
	v_add_f32_e32 v52, v52, v60
	v_add_f32_e32 v53, v53, v2
	v_cvt_pk_bf16_f32 v0, v4, v0
	v_fma_f32 v4, v68, v6, -v59
	v_fma_f32 v1, v68, v7, -v1
	v_add_f32_e32 v54, v54, v61
	v_add_f32_e32 v55, v55, v3
	v_cvt_pk_bf16_f32 v1, v4, v1
	v_fma_f32 v4, v68, v52, -v60
	v_fma_f32 v2, v68, v53, -v2
	v_cvt_pk_bf16_f32 v2, v4, v2
	v_fma_f32 v4, v68, v54, -v61
	v_fma_f32 v3, v68, v55, -v3
	v_cvt_pk_bf16_f32 v3, v4, v3
	v_lshlrev_b64 v[4:5], 10, v[56:57]
	v_lshl_add_u64 v[4:5], v[10:11], 0, v[4:5]
	global_store_dwordx4 v[4:5], v[0:3], off
	v_xor_b32_e32 v4, 2, v207
	v_xor_b32_e32 v6, 1, v207
	v_and_b32_e32 v0, 64, v207
	v_add_u32_e32 v5, 64, v0
	v_xor_b32_e32 v0, 32, v207
	v_cmp_lt_i32_e32 vcc, v0, v5
	v_xor_b32_e32 v1, 16, v207
	v_xor_b32_e32 v2, 8, v207
	v_cndmask_b32_e32 v0, v207, v0, vcc
	v_cmp_lt_i32_e32 vcc, v1, v5
	v_xor_b32_e32 v3, 4, v207
	v_lshlrev_b32_e32 v0, 2, v0
	v_cndmask_b32_e32 v1, v207, v1, vcc
	v_cmp_lt_i32_e32 vcc, v2, v5
	v_lshlrev_b32_e32 v1, 2, v1
	s_nop 0
	v_cndmask_b32_e32 v2, v207, v2, vcc
	v_cmp_lt_i32_e32 vcc, v3, v5
	v_lshlrev_b32_e32 v2, 2, v2
	s_nop 0
	v_cndmask_b32_e32 v3, v207, v3, vcc
	v_cmp_lt_i32_e32 vcc, v4, v5
	v_lshlrev_b32_e32 v3, 2, v3
	s_nop 0
	v_cndmask_b32_e32 v4, v207, v4, vcc
	v_cmp_lt_i32_e32 vcc, v6, v5
	v_lshlrev_b32_e32 v4, 2, v4
	s_nop 0
	v_cndmask_b32_e32 v5, v207, v6, vcc
	v_lshl_add_u64 v[84:85], s[4:5], 0, v[12:13]
	v_mad_u64_u32 v[86:87], s[16:17], v84, s45, v[44:45]
	v_mad_i32_i24 v87, v85, s45, v87
	global_load_dwordx4 v[84:87], v[86:87], off offset:2048
	v_lshl_add_u64 v[88:89], s[4:5], 0, v[14:15]
	v_mad_u64_u32 v[90:91], s[16:17], v88, s45, v[44:45]
	v_mad_i32_i24 v91, v89, s45, v91
	global_load_dwordx4 v[88:91], v[90:91], off offset:2048
	v_lshl_add_u64 v[92:93], s[4:5], 0, v[16:17]
	v_mad_u64_u32 v[94:95], s[16:17], v92, s45, v[44:45]
	v_mad_i32_i24 v95, v93, s45, v95
	global_load_dwordx4 v[92:95], v[94:95], off offset:2048
	v_lshl_add_u64 v[96:97], s[4:5], 0, v[18:19]
	v_mad_u64_u32 v[98:99], s[16:17], v96, s45, v[44:45]
	v_mad_i32_i24 v99, v97, s45, v99
	global_load_dwordx4 v[96:99], v[98:99], off offset:2048
	v_lshl_add_u64 v[100:101], s[4:5], 0, v[20:21]
	v_mad_u64_u32 v[102:103], s[16:17], v100, s45, v[44:45]
	v_mad_i32_i24 v103, v101, s45, v103
	global_load_dwordx4 v[100:103], v[102:103], off offset:2048
	v_lshl_add_u64 v[104:105], s[4:5], 0, v[22:23]
	v_mad_u64_u32 v[106:107], s[16:17], v104, s45, v[44:45]
	v_mad_i32_i24 v107, v105, s45, v107
	global_load_dwordx4 v[104:107], v[106:107], off offset:2048
	v_lshl_add_u64 v[108:109], s[4:5], 0, v[24:25]
	v_mad_u64_u32 v[110:111], s[16:17], v108, s45, v[44:45]
	v_mad_i32_i24 v111, v109, s45, v111
	global_load_dwordx4 v[108:111], v[110:111], off offset:2048
	v_lshl_add_u64 v[112:113], s[4:5], 0, v[26:27]
	v_mad_u64_u32 v[114:115], s[16:17], v112, s45, v[44:45]
	v_mad_i32_i24 v115, v113, s45, v115
	global_load_dwordx4 v[112:115], v[114:115], off offset:2048
	v_lshl_add_u64 v[116:117], s[4:5], 0, v[28:29]
	v_mad_u64_u32 v[118:119], s[16:17], v116, s45, v[44:45]
	v_mad_i32_i24 v119, v117, s45, v119
	global_load_dwordx4 v[116:119], v[118:119], off offset:2048
	v_lshl_add_u64 v[120:121], s[4:5], 0, v[30:31]
	v_mad_u64_u32 v[122:123], s[16:17], v120, s45, v[44:45]
	v_mad_i32_i24 v123, v121, s45, v123
	global_load_dwordx4 v[120:123], v[122:123], off offset:2048
	v_lshl_add_u64 v[124:125], s[4:5], 0, v[32:33]
	v_mad_u64_u32 v[126:127], s[16:17], v124, s45, v[44:45]
	v_mad_i32_i24 v127, v125, s45, v127
	global_load_dwordx4 v[124:127], v[126:127], off offset:2048
	v_lshl_add_u64 v[128:129], s[4:5], 0, v[34:35]
	v_mad_u64_u32 v[130:131], s[16:17], v128, s45, v[44:45]
	v_mad_i32_i24 v131, v129, s45, v131
	global_load_dwordx4 v[128:131], v[130:131], off offset:2048
	v_lshl_add_u64 v[132:133], s[4:5], 0, v[36:37]
	v_mad_u64_u32 v[134:135], s[16:17], v132, s45, v[44:45]
	v_mad_i32_i24 v135, v133, s45, v135
	global_load_dwordx4 v[132:135], v[134:135], off offset:2048
	v_lshl_add_u64 v[136:137], s[4:5], 0, v[38:39]
	v_mad_u64_u32 v[138:139], s[16:17], v136, s45, v[44:45]
	v_mad_i32_i24 v139, v137, s45, v139
	global_load_dwordx4 v[136:139], v[138:139], off offset:2048
	v_lshl_add_u64 v[140:141], s[4:5], 0, v[40:41]
	v_mad_u64_u32 v[142:143], s[16:17], v140, s45, v[44:45]
	v_mad_i32_i24 v143, v141, s45, v143
	global_load_dwordx4 v[140:143], v[142:143], off offset:2048
	v_lshl_add_u64 v[144:145], s[4:5], 0, v[42:43]
	v_mad_u64_u32 v[146:147], s[16:17], v144, s45, v[44:45]
	v_mad_i32_i24 v147, v145, s45, v147
	global_load_dwordx4 v[144:147], v[146:147], off offset:2048
	s_waitcnt vmcnt(0)
; __device__ __forceinline__ void UNPACK8(const u32x4 q, float (&f)[8]) { f[0] = bflo(q.x); f[1] = bfhi(q.x); f[2] = bflo(q.y); f[3] = bfhi(q.y); f[4] = bflo(q.z); f[5] = bfhi(q.z); f[6] = bflo(q.w); f[7] = bfhi(q.w); }
; __device__ __forceinline__ void sguprep_chunk(PCP p, int j, LAS unsigned char* lds, int it, int tid) {
;     ...
;         for (int s0 = 0; s0 < 16; ++s0) { const int s = wid * 16 + s0; const u32x4 vw = *(const u32x4*)(proj + (T0 + s) * 1536 + 1024 + lane * 8); float v[8]; UNPACK8(vw, v); float ss = 0.f;
; #pragma unroll
;             for (int e = 0; e < 8; ++e) ss += v[e] * v[e];
;             ss = wave_sum(ss); if (lane == 0) rstd[s] = rsqrtf(ss * (1.0f / 512.0f) + EPS); }
	v_lshlrev_b32_e32 v5, 2, v5
	v_and_b32_e32 v7, 0xffff0000, v84
	v_lshlrev_b32_e32 v6, 16, v84
	v_mul_f32_e32 v7, v7, v7
	v_lshlrev_b32_e32 v52, 16, v85
	v_fmac_f32_e32 v7, v6, v6
	v_and_b32_e32 v53, 0xffff0000, v85
	v_fmac_f32_e32 v7, v52, v52
	v_lshlrev_b32_e32 v56, 16, v86
	v_fmac_f32_e32 v7, v53, v53
	v_and_b32_e32 v54, 0xffff0000, v86
	v_fmac_f32_e32 v7, v56, v56
	v_lshlrev_b32_e32 v57, 16, v87
	v_fmac_f32_e32 v7, v54, v54
	v_and_b32_e32 v55, 0xffff0000, v87
	v_fmac_f32_e32 v7, v57, v57
	v_fmac_f32_e32 v7, v55, v55
	v_mov_b32_e32 v84, v7
	v_and_b32_e32 v7, 0xffff0000, v88
	v_lshlrev_b32_e32 v6, 16, v88
	v_mul_f32_e32 v7, v7, v7
	v_lshlrev_b32_e32 v52, 16, v89
	v_fmac_f32_e32 v7, v6, v6
	v_and_b32_e32 v53, 0xffff0000, v89
	v_fmac_f32_e32 v7, v52, v52
	v_lshlrev_b32_e32 v56, 16, v90
	v_fmac_f32_e32 v7, v53, v53
	v_and_b32_e32 v54, 0xffff0000, v90
	v_fmac_f32_e32 v7, v56, v56
	v_lshlrev_b32_e32 v57, 16, v91
	v_fmac_f32_e32 v7, v54, v54
	v_and_b32_e32 v55, 0xffff0000, v91
	v_fmac_f32_e32 v7, v57, v57
	v_fmac_f32_e32 v7, v55, v55
	v_mov_b32_e32 v88, v7
	v_and_b32_e32 v7, 0xffff0000, v92
	v_lshlrev_b32_e32 v6, 16, v92
	v_mul_f32_e32 v7, v7, v7
	v_lshlrev_b32_e32 v52, 16, v93
	v_fmac_f32_e32 v7, v6, v6
	v_and_b32_e32 v53, 0xffff0000, v93
	v_fmac_f32_e32 v7, v52, v52
	v_lshlrev_b32_e32 v56, 16, v94
	v_fmac_f32_e32 v7, v53, v53
	v_and_b32_e32 v54, 0xffff0000, v94
	v_fmac_f32_e32 v7, v56, v56
	v_lshlrev_b32_e32 v57, 16, v95
	v_fmac_f32_e32 v7, v54, v54
	v_and_b32_e32 v55, 0xffff0000, v95
	v_fmac_f32_e32 v7, v57, v57
	v_fmac_f32_e32 v7, v55, v55
	v_mov_b32_e32 v92, v7
	v_and_b32_e32 v7, 0xffff0000, v96
	v_lshlrev_b32_e32 v6, 16, v96
	v_mul_f32_e32 v7, v7, v7
	v_lshlrev_b32_e32 v52, 16, v97
	v_fmac_f32_e32 v7, v6, v6
	v_and_b32_e32 v53, 0xffff0000, v97
	v_fmac_f32_e32 v7, v52, v52
	v_lshlrev_b32_e32 v56, 16, v98
	v_fmac_f32_e32 v7, v53, v53
	v_and_b32_e32 v54, 0xffff0000, v98
	v_fmac_f32_e32 v7, v56, v56
	v_lshlrev_b32_e32 v57, 16, v99
	v_fmac_f32_e32 v7, v54, v54
	v_and_b32_e32 v55, 0xffff0000, v99
	v_fmac_f32_e32 v7, v57, v57
	v_fmac_f32_e32 v7, v55, v55
	v_mov_b32_e32 v96, v7
	v_and_b32_e32 v7, 0xffff0000, v100
	v_lshlrev_b32_e32 v6, 16, v100
	v_mul_f32_e32 v7, v7, v7
	v_lshlrev_b32_e32 v52, 16, v101
	v_fmac_f32_e32 v7, v6, v6
	v_and_b32_e32 v53, 0xffff0000, v101
	v_fmac_f32_e32 v7, v52, v52
	v_lshlrev_b32_e32 v56, 16, v102
	v_fmac_f32_e32 v7, v53, v53
	v_and_b32_e32 v54, 0xffff0000, v102
	v_fmac_f32_e32 v7, v56, v56
	v_lshlrev_b32_e32 v57, 16, v103
	v_fmac_f32_e32 v7, v54, v54
	v_and_b32_e32 v55, 0xffff0000, v103
	v_fmac_f32_e32 v7, v57, v57
	v_fmac_f32_e32 v7, v55, v55
	v_mov_b32_e32 v100, v7
	v_and_b32_e32 v7, 0xffff0000, v104
	v_lshlrev_b32_e32 v6, 16, v104
	v_mul_f32_e32 v7, v7, v7
	v_lshlrev_b32_e32 v52, 16, v105
	v_fmac_f32_e32 v7, v6, v6
	v_and_b32_e32 v53, 0xffff0000, v105
	v_fmac_f32_e32 v7, v52, v52
	v_lshlrev_b32_e32 v56, 16, v106
	v_fmac_f32_e32 v7, v53, v53
	v_and_b32_e32 v54, 0xffff0000, v106
	v_fmac_f32_e32 v7, v56, v56
	v_lshlrev_b32_e32 v57, 16, v107
	v_fmac_f32_e32 v7, v54, v54
	v_and_b32_e32 v55, 0xffff0000, v107
	v_fmac_f32_e32 v7, v57, v57
	v_fmac_f32_e32 v7, v55, v55
	v_mov_b32_e32 v104, v7
	v_and_b32_e32 v7, 0xffff0000, v108
	v_lshlrev_b32_e32 v6, 16, v108
	v_mul_f32_e32 v7, v7, v7
	v_lshlrev_b32_e32 v52, 16, v109
	v_fmac_f32_e32 v7, v6, v6
	v_and_b32_e32 v53, 0xffff0000, v109
	v_fmac_f32_e32 v7, v52, v52
	v_lshlrev_b32_e32 v56, 16, v110
	v_fmac_f32_e32 v7, v53, v53
	v_and_b32_e32 v54, 0xffff0000, v110
	v_fmac_f32_e32 v7, v56, v56
	v_lshlrev_b32_e32 v57, 16, v111
	v_fmac_f32_e32 v7, v54, v54
	v_and_b32_e32 v55, 0xffff0000, v111
	v_fmac_f32_e32 v7, v57, v57
	v_fmac_f32_e32 v7, v55, v55
	v_mov_b32_e32 v108, v7
	v_and_b32_e32 v7, 0xffff0000, v112
	v_lshlrev_b32_e32 v6, 16, v112
	v_mul_f32_e32 v7, v7, v7
	v_lshlrev_b32_e32 v52, 16, v113
	v_fmac_f32_e32 v7, v6, v6
	v_and_b32_e32 v53, 0xffff0000, v113
	v_fmac_f32_e32 v7, v52, v52
	v_lshlrev_b32_e32 v56, 16, v114
	v_fmac_f32_e32 v7, v53, v53
	v_and_b32_e32 v54, 0xffff0000, v114
	v_fmac_f32_e32 v7, v56, v56
	v_lshlrev_b32_e32 v57, 16, v115
	v_fmac_f32_e32 v7, v54, v54
	v_and_b32_e32 v55, 0xffff0000, v115
	v_fmac_f32_e32 v7, v57, v57
	v_fmac_f32_e32 v7, v55, v55
	v_mov_b32_e32 v112, v7
	v_and_b32_e32 v7, 0xffff0000, v116
	v_lshlrev_b32_e32 v6, 16, v116
	v_mul_f32_e32 v7, v7, v7
	v_lshlrev_b32_e32 v52, 16, v117
	v_fmac_f32_e32 v7, v6, v6
	v_and_b32_e32 v53, 0xffff0000, v117
	v_fmac_f32_e32 v7, v52, v52
	v_lshlrev_b32_e32 v56, 16, v118
	v_fmac_f32_e32 v7, v53, v53
	v_and_b32_e32 v54, 0xffff0000, v118
	v_fmac_f32_e32 v7, v56, v56
	v_lshlrev_b32_e32 v57, 16, v119
	v_fmac_f32_e32 v7, v54, v54
	v_and_b32_e32 v55, 0xffff0000, v119
	v_fmac_f32_e32 v7, v57, v57
	v_fmac_f32_e32 v7, v55, v55
	v_mov_b32_e32 v116, v7
	v_and_b32_e32 v7, 0xffff0000, v120
	v_lshlrev_b32_e32 v6, 16, v120
	v_mul_f32_e32 v7, v7, v7
	v_lshlrev_b32_e32 v52, 16, v121
	v_fmac_f32_e32 v7, v6, v6
	v_and_b32_e32 v53, 0xffff0000, v121
	v_fmac_f32_e32 v7, v52, v52
	v_lshlrev_b32_e32 v56, 16, v122
	v_fmac_f32_e32 v7, v53, v53
	v_and_b32_e32 v54, 0xffff0000, v122
	v_fmac_f32_e32 v7, v56, v56
	v_lshlrev_b32_e32 v57, 16, v123
	v_fmac_f32_e32 v7, v54, v54
	v_and_b32_e32 v55, 0xffff0000, v123
	v_fmac_f32_e32 v7, v57, v57
	v_fmac_f32_e32 v7, v55, v55
	v_mov_b32_e32 v120, v7
	v_and_b32_e32 v7, 0xffff0000, v124
	v_lshlrev_b32_e32 v6, 16, v124
	v_mul_f32_e32 v7, v7, v7
	v_lshlrev_b32_e32 v52, 16, v125
	v_fmac_f32_e32 v7, v6, v6
	v_and_b32_e32 v53, 0xffff0000, v125
	v_fmac_f32_e32 v7, v52, v52
	v_lshlrev_b32_e32 v56, 16, v126
	v_fmac_f32_e32 v7, v53, v53
	v_and_b32_e32 v54, 0xffff0000, v126
	v_fmac_f32_e32 v7, v56, v56
; __device__ __forceinline__ void UNPACK8(const u32x4 q, float (&f)[8]) { f[0] = bflo(q.x); f[1] = bfhi(q.x); f[2] = bflo(q.y); f[3] = bfhi(q.y); f[4] = bflo(q.z); f[5] = bfhi(q.z); f[6] = bflo(q.w); f[7] = bfhi(q.w); }
; __device__ __forceinline__ float wave_sum(float v) {
; #pragma unroll
;     for (int o = 32; o >= 1; o >>= 1) v += __shfl_xor(v, o);
;     return v;
; __device__ __forceinline__ void sguprep_chunk(PCP p, int j, LAS unsigned char* lds, int it, int tid) {
;     ...
;         for (int s0 = 0; s0 < 16; ++s0) { const int s = wid * 16 + s0; const u32x4 vw = *(const u32x4*)(proj + (T0 + s) * 1536 + 1024 + lane * 8); float v[8]; UNPACK8(vw, v); float ss = 0.f;
; #pragma unroll
;             for (int e = 0; e < 8; ++e) ss += v[e] * v[e];
;             ss = wave_sum(ss); if (lane == 0) rstd[s] = rsqrtf(ss * (1.0f / 512.0f) + EPS); }
	v_lshlrev_b32_e32 v57, 16, v127
	v_fmac_f32_e32 v7, v54, v54
	v_and_b32_e32 v55, 0xffff0000, v127
	v_fmac_f32_e32 v7, v57, v57
	v_fmac_f32_e32 v7, v55, v55
	v_mov_b32_e32 v124, v7
	v_and_b32_e32 v7, 0xffff0000, v128
	v_lshlrev_b32_e32 v6, 16, v128
	v_mul_f32_e32 v7, v7, v7
	v_lshlrev_b32_e32 v52, 16, v129
	v_fmac_f32_e32 v7, v6, v6
	v_and_b32_e32 v53, 0xffff0000, v129
	v_fmac_f32_e32 v7, v52, v52
	v_lshlrev_b32_e32 v56, 16, v130
	v_fmac_f32_e32 v7, v53, v53
	v_and_b32_e32 v54, 0xffff0000, v130
	v_fmac_f32_e32 v7, v56, v56
	v_lshlrev_b32_e32 v57, 16, v131
	v_fmac_f32_e32 v7, v54, v54
	v_and_b32_e32 v55, 0xffff0000, v131
	v_fmac_f32_e32 v7, v57, v57
	v_fmac_f32_e32 v7, v55, v55
	v_mov_b32_e32 v128, v7
	v_and_b32_e32 v7, 0xffff0000, v132
	v_lshlrev_b32_e32 v6, 16, v132
	v_mul_f32_e32 v7, v7, v7
	v_lshlrev_b32_e32 v52, 16, v133
	v_fmac_f32_e32 v7, v6, v6
	v_and_b32_e32 v53, 0xffff0000, v133
	v_fmac_f32_e32 v7, v52, v52
	v_lshlrev_b32_e32 v56, 16, v134
	v_fmac_f32_e32 v7, v53, v53
	v_and_b32_e32 v54, 0xffff0000, v134
	v_fmac_f32_e32 v7, v56, v56
	v_lshlrev_b32_e32 v57, 16, v135
	v_fmac_f32_e32 v7, v54, v54
	v_and_b32_e32 v55, 0xffff0000, v135
	v_fmac_f32_e32 v7, v57, v57
	v_fmac_f32_e32 v7, v55, v55
	v_mov_b32_e32 v132, v7
	v_and_b32_e32 v7, 0xffff0000, v136
	v_lshlrev_b32_e32 v6, 16, v136
	v_mul_f32_e32 v7, v7, v7
	v_lshlrev_b32_e32 v52, 16, v137
	v_fmac_f32_e32 v7, v6, v6
	v_and_b32_e32 v53, 0xffff0000, v137
	v_fmac_f32_e32 v7, v52, v52
	v_lshlrev_b32_e32 v56, 16, v138
	v_fmac_f32_e32 v7, v53, v53
	v_and_b32_e32 v54, 0xffff0000, v138
	v_fmac_f32_e32 v7, v56, v56
	v_lshlrev_b32_e32 v57, 16, v139
	v_fmac_f32_e32 v7, v54, v54
	v_and_b32_e32 v55, 0xffff0000, v139
	v_fmac_f32_e32 v7, v57, v57
	v_fmac_f32_e32 v7, v55, v55
	v_mov_b32_e32 v136, v7
	v_and_b32_e32 v7, 0xffff0000, v140
	v_lshlrev_b32_e32 v6, 16, v140
	v_mul_f32_e32 v7, v7, v7
	v_lshlrev_b32_e32 v52, 16, v141
	v_fmac_f32_e32 v7, v6, v6
	v_and_b32_e32 v53, 0xffff0000, v141
	v_fmac_f32_e32 v7, v52, v52
	v_lshlrev_b32_e32 v56, 16, v142
	v_fmac_f32_e32 v7, v53, v53
	v_and_b32_e32 v54, 0xffff0000, v142
	v_fmac_f32_e32 v7, v56, v56
	v_lshlrev_b32_e32 v57, 16, v143
	v_fmac_f32_e32 v7, v54, v54
	v_and_b32_e32 v55, 0xffff0000, v143
	v_fmac_f32_e32 v7, v57, v57
	v_fmac_f32_e32 v7, v55, v55
	v_mov_b32_e32 v140, v7
	v_and_b32_e32 v7, 0xffff0000, v144
	v_lshlrev_b32_e32 v6, 16, v144
	v_mul_f32_e32 v7, v7, v7
	v_lshlrev_b32_e32 v52, 16, v145
	v_fmac_f32_e32 v7, v6, v6
	v_and_b32_e32 v53, 0xffff0000, v145
	v_fmac_f32_e32 v7, v52, v52
	v_lshlrev_b32_e32 v56, 16, v146
	v_fmac_f32_e32 v7, v53, v53
	v_and_b32_e32 v54, 0xffff0000, v146
	v_fmac_f32_e32 v7, v56, v56
	v_lshlrev_b32_e32 v57, 16, v147
	v_fmac_f32_e32 v7, v54, v54
	v_and_b32_e32 v55, 0xffff0000, v147
	v_fmac_f32_e32 v7, v57, v57
	v_fmac_f32_e32 v7, v55, v55
	v_mov_b32_e32 v144, v7
	ds_bpermute_b32 v85, v0, v84
	ds_bpermute_b32 v89, v0, v88
	ds_bpermute_b32 v93, v0, v92
	ds_bpermute_b32 v97, v0, v96
	ds_bpermute_b32 v101, v0, v100
	ds_bpermute_b32 v105, v0, v104
	ds_bpermute_b32 v109, v0, v108
	ds_bpermute_b32 v113, v0, v112
	ds_bpermute_b32 v117, v0, v116
	ds_bpermute_b32 v121, v0, v120
	ds_bpermute_b32 v125, v0, v124
	ds_bpermute_b32 v129, v0, v128
	ds_bpermute_b32 v133, v0, v132
	ds_bpermute_b32 v137, v0, v136
	ds_bpermute_b32 v141, v0, v140
	ds_bpermute_b32 v145, v0, v144
	s_waitcnt lgkmcnt(0)
	v_add_f32_e32 v84, v84, v85
	v_add_f32_e32 v88, v88, v89
	v_add_f32_e32 v92, v92, v93
	v_add_f32_e32 v96, v96, v97
	v_add_f32_e32 v100, v100, v101
	v_add_f32_e32 v104, v104, v105
	v_add_f32_e32 v108, v108, v109
	v_add_f32_e32 v112, v112, v113
	v_add_f32_e32 v116, v116, v117
	v_add_f32_e32 v120, v120, v121
	v_add_f32_e32 v124, v124, v125
	v_add_f32_e32 v128, v128, v129
	v_add_f32_e32 v132, v132, v133
	v_add_f32_e32 v136, v136, v137
	v_add_f32_e32 v140, v140, v141
	v_add_f32_e32 v144, v144, v145
	ds_bpermute_b32 v85, v1, v84
	ds_bpermute_b32 v89, v1, v88
	ds_bpermute_b32 v93, v1, v92
	ds_bpermute_b32 v97, v1, v96
	ds_bpermute_b32 v101, v1, v100
	ds_bpermute_b32 v105, v1, v104
	ds_bpermute_b32 v109, v1, v108
	ds_bpermute_b32 v113, v1, v112
	ds_bpermute_b32 v117, v1, v116
	ds_bpermute_b32 v121, v1, v120
	ds_bpermute_b32 v125, v1, v124
	ds_bpermute_b32 v129, v1, v128
	ds_bpermute_b32 v133, v1, v132
	ds_bpermute_b32 v137, v1, v136
	ds_bpermute_b32 v141, v1, v140
	ds_bpermute_b32 v145, v1, v144
	s_waitcnt lgkmcnt(0)
	v_add_f32_e32 v84, v84, v85
	v_add_f32_e32 v88, v88, v89
	v_add_f32_e32 v92, v92, v93
	v_add_f32_e32 v96, v96, v97
	v_add_f32_e32 v100, v100, v101
	v_add_f32_e32 v104, v104, v105
	v_add_f32_e32 v108, v108, v109
	v_add_f32_e32 v112, v112, v113
	v_add_f32_e32 v116, v116, v117
	v_add_f32_e32 v120, v120, v121
	v_add_f32_e32 v124, v124, v125
	v_add_f32_e32 v128, v128, v129
	v_add_f32_e32 v132, v132, v133
	v_add_f32_e32 v136, v136, v137
	v_add_f32_e32 v140, v140, v141
	v_add_f32_e32 v144, v144, v145
	ds_bpermute_b32 v85, v2, v84
	ds_bpermute_b32 v89, v2, v88
	ds_bpermute_b32 v93, v2, v92
	ds_bpermute_b32 v97, v2, v96
	ds_bpermute_b32 v101, v2, v100
	ds_bpermute_b32 v105, v2, v104
	ds_bpermute_b32 v109, v2, v108
	ds_bpermute_b32 v113, v2, v112
	ds_bpermute_b32 v117, v2, v116
	ds_bpermute_b32 v121, v2, v120
	ds_bpermute_b32 v125, v2, v124
	ds_bpermute_b32 v129, v2, v128
	ds_bpermute_b32 v133, v2, v132
	ds_bpermute_b32 v137, v2, v136
	ds_bpermute_b32 v141, v2, v140
	ds_bpermute_b32 v145, v2, v144
	s_waitcnt lgkmcnt(0)
; __device__ __forceinline__ float wave_sum(float v) {
; #pragma unroll
;     for (int o = 32; o >= 1; o >>= 1) v += __shfl_xor(v, o);
;     return v;
	v_add_f32_e32 v84, v84, v85
	v_add_f32_e32 v88, v88, v89
	v_add_f32_e32 v92, v92, v93
	v_add_f32_e32 v96, v96, v97
	v_add_f32_e32 v100, v100, v101
	v_add_f32_e32 v104, v104, v105
	v_add_f32_e32 v108, v108, v109
	v_add_f32_e32 v112, v112, v113
	v_add_f32_e32 v116, v116, v117
	v_add_f32_e32 v120, v120, v121
	v_add_f32_e32 v124, v124, v125
	v_add_f32_e32 v128, v128, v129
	v_add_f32_e32 v132, v132, v133
	v_add_f32_e32 v136, v136, v137
	v_add_f32_e32 v140, v140, v141
	v_add_f32_e32 v144, v144, v145
	ds_bpermute_b32 v85, v3, v84
	ds_bpermute_b32 v89, v3, v88
	ds_bpermute_b32 v93, v3, v92
	ds_bpermute_b32 v97, v3, v96
	ds_bpermute_b32 v101, v3, v100
	ds_bpermute_b32 v105, v3, v104
	ds_bpermute_b32 v109, v3, v108
	ds_bpermute_b32 v113, v3, v112
	ds_bpermute_b32 v117, v3, v116
	ds_bpermute_b32 v121, v3, v120
	ds_bpermute_b32 v125, v3, v124
	ds_bpermute_b32 v129, v3, v128
	ds_bpermute_b32 v133, v3, v132
	ds_bpermute_b32 v137, v3, v136
	ds_bpermute_b32 v141, v3, v140
	ds_bpermute_b32 v145, v3, v144
	s_waitcnt lgkmcnt(0)
	v_add_f32_e32 v84, v84, v85
	v_add_f32_e32 v88, v88, v89
	v_add_f32_e32 v92, v92, v93
	v_add_f32_e32 v96, v96, v97
	v_add_f32_e32 v100, v100, v101
	v_add_f32_e32 v104, v104, v105
	v_add_f32_e32 v108, v108, v109
	v_add_f32_e32 v112, v112, v113
	v_add_f32_e32 v116, v116, v117
	v_add_f32_e32 v120, v120, v121
	v_add_f32_e32 v124, v124, v125
	v_add_f32_e32 v128, v128, v129
	v_add_f32_e32 v132, v132, v133
	v_add_f32_e32 v136, v136, v137
	v_add_f32_e32 v140, v140, v141
	v_add_f32_e32 v144, v144, v145
	ds_bpermute_b32 v85, v4, v84
	ds_bpermute_b32 v89, v4, v88
	ds_bpermute_b32 v93, v4, v92
	ds_bpermute_b32 v97, v4, v96
	ds_bpermute_b32 v101, v4, v100
	ds_bpermute_b32 v105, v4, v104
	ds_bpermute_b32 v109, v4, v108
	ds_bpermute_b32 v113, v4, v112
	ds_bpermute_b32 v117, v4, v116
	ds_bpermute_b32 v121, v4, v120
	ds_bpermute_b32 v125, v4, v124
	ds_bpermute_b32 v129, v4, v128
	ds_bpermute_b32 v133, v4, v132
	ds_bpermute_b32 v137, v4, v136
	ds_bpermute_b32 v141, v4, v140
	ds_bpermute_b32 v145, v4, v144
	s_waitcnt lgkmcnt(0)
	v_add_f32_e32 v84, v84, v85
	v_add_f32_e32 v88, v88, v89
	v_add_f32_e32 v92, v92, v93
	v_add_f32_e32 v96, v96, v97
	v_add_f32_e32 v100, v100, v101
	v_add_f32_e32 v104, v104, v105
	v_add_f32_e32 v108, v108, v109
	v_add_f32_e32 v112, v112, v113
	v_add_f32_e32 v116, v116, v117
	v_add_f32_e32 v120, v120, v121
	v_add_f32_e32 v124, v124, v125
	v_add_f32_e32 v128, v128, v129
	v_add_f32_e32 v132, v132, v133
	v_add_f32_e32 v136, v136, v137
	v_add_f32_e32 v140, v140, v141
	v_add_f32_e32 v144, v144, v145
	ds_bpermute_b32 v85, v5, v84
	ds_bpermute_b32 v89, v5, v88
	ds_bpermute_b32 v93, v5, v92
	ds_bpermute_b32 v97, v5, v96
	ds_bpermute_b32 v101, v5, v100
	ds_bpermute_b32 v105, v5, v104
	ds_bpermute_b32 v109, v5, v108
	ds_bpermute_b32 v113, v5, v112
	ds_bpermute_b32 v117, v5, v116
	ds_bpermute_b32 v121, v5, v120
	ds_bpermute_b32 v125, v5, v124
	ds_bpermute_b32 v129, v5, v128
	ds_bpermute_b32 v133, v5, v132
	ds_bpermute_b32 v137, v5, v136
	ds_bpermute_b32 v141, v5, v140
	ds_bpermute_b32 v145, v5, v144
	s_waitcnt lgkmcnt(0)
; __device__ __forceinline__ void UNPACK8(const u32x4 q, float (&f)[8]) { f[0] = bflo(q.x); f[1] = bfhi(q.x); f[2] = bflo(q.y); f[3] = bfhi(q.y); f[4] = bflo(q.z); f[5] = bfhi(q.z); f[6] = bflo(q.w); f[7] = bfhi(q.w); }
; __device__ __forceinline__ void sguprep_chunk(PCP p, int j, LAS unsigned char* lds, int it, int tid) {
;     ...
;         for (int s0 = 0; s0 < 16; ++s0) { const int s = wid * 16 + s0; const u32x4 vw = *(const u32x4*)(proj + (T0 + s) * 1536 + 1024 + lane * 8); float v[8]; UNPACK8(vw, v); float ss = 0.f;
; #pragma unroll
;             for (int e = 0; e < 8; ++e) ss += v[e] * v[e];
;             ss = wave_sum(ss); if (lane == 0) rstd[s] = rsqrtf(ss * (1.0f / 512.0f) + EPS); }
	v_add_f32_e32 v84, v84, v85
	v_add_f32_e32 v88, v88, v89
	v_add_f32_e32 v92, v92, v93
	v_add_f32_e32 v96, v96, v97
	v_add_f32_e32 v100, v100, v101
	v_add_f32_e32 v104, v104, v105
	v_add_f32_e32 v108, v108, v109
	v_add_f32_e32 v112, v112, v113
	v_add_f32_e32 v116, v116, v117
	v_add_f32_e32 v120, v120, v121
	v_add_f32_e32 v124, v124, v125
	v_add_f32_e32 v128, v128, v129
	v_add_f32_e32 v132, v132, v133
	v_add_f32_e32 v136, v136, v137
	v_add_f32_e32 v140, v140, v141
	v_add_f32_e32 v144, v144, v145
	s_and_saveexec_b64 s[16:17], s[14:15]
	v_fmamk_f32 v6, v84, 0x3b000000, v208
	v_mul_f32_e32 v7, 0x4b800000, v6
	v_cmp_gt_f32_e32 vcc, s44, v6
	s_nop 1
	v_cndmask_b32_e32 v6, v6, v7, vcc
	v_rsq_f32_e32 v6, v6
	s_nop 0
	v_mul_f32_e32 v7, 0x45800000, v6
	v_cndmask_b32_e32 v6, v6, v7, vcc
	ds_write_b32 v69, v6
	v_fmamk_f32 v6, v88, 0x3b000000, v208
	v_mul_f32_e32 v7, 0x4b800000, v6
	v_cmp_gt_f32_e32 vcc, s44, v6
	s_nop 1
	v_cndmask_b32_e32 v6, v6, v7, vcc
	v_rsq_f32_e32 v6, v6
	s_nop 0
	v_mul_f32_e32 v7, 0x45800000, v6
	v_cndmask_b32_e32 v6, v6, v7, vcc
	ds_write_b32 v69, v6 offset:4
	v_fmamk_f32 v6, v92, 0x3b000000, v208
	v_mul_f32_e32 v7, 0x4b800000, v6
	v_cmp_gt_f32_e32 vcc, s44, v6
	s_nop 1
	v_cndmask_b32_e32 v6, v6, v7, vcc
	v_rsq_f32_e32 v6, v6
	s_nop 0
	v_mul_f32_e32 v7, 0x45800000, v6
	v_cndmask_b32_e32 v6, v6, v7, vcc
	ds_write_b32 v69, v6 offset:8
	v_fmamk_f32 v6, v96, 0x3b000000, v208
	v_mul_f32_e32 v7, 0x4b800000, v6
	v_cmp_gt_f32_e32 vcc, s44, v6
	s_nop 1
	v_cndmask_b32_e32 v6, v6, v7, vcc
	v_rsq_f32_e32 v6, v6
	s_nop 0
	v_mul_f32_e32 v7, 0x45800000, v6
	v_cndmask_b32_e32 v6, v6, v7, vcc
	ds_write_b32 v69, v6 offset:12
	v_fmamk_f32 v6, v100, 0x3b000000, v208
	v_mul_f32_e32 v7, 0x4b800000, v6
	v_cmp_gt_f32_e32 vcc, s44, v6
	s_nop 1
	v_cndmask_b32_e32 v6, v6, v7, vcc
	v_rsq_f32_e32 v6, v6
	s_nop 0
	v_mul_f32_e32 v7, 0x45800000, v6
	v_cndmask_b32_e32 v6, v6, v7, vcc
	ds_write_b32 v69, v6 offset:16
	v_fmamk_f32 v6, v104, 0x3b000000, v208
	v_mul_f32_e32 v7, 0x4b800000, v6
	v_cmp_gt_f32_e32 vcc, s44, v6
	s_nop 1
	v_cndmask_b32_e32 v6, v6, v7, vcc
	v_rsq_f32_e32 v6, v6
	s_nop 0
	v_mul_f32_e32 v7, 0x45800000, v6
	v_cndmask_b32_e32 v6, v6, v7, vcc
	ds_write_b32 v69, v6 offset:20
	v_fmamk_f32 v6, v108, 0x3b000000, v208
	v_mul_f32_e32 v7, 0x4b800000, v6
	v_cmp_gt_f32_e32 vcc, s44, v6
	s_nop 1
	v_cndmask_b32_e32 v6, v6, v7, vcc
	v_rsq_f32_e32 v6, v6
	s_nop 0
	v_mul_f32_e32 v7, 0x45800000, v6
	v_cndmask_b32_e32 v6, v6, v7, vcc
	ds_write_b32 v69, v6 offset:24
	v_fmamk_f32 v6, v112, 0x3b000000, v208
	v_mul_f32_e32 v7, 0x4b800000, v6
	v_cmp_gt_f32_e32 vcc, s44, v6
	s_nop 1
	v_cndmask_b32_e32 v6, v6, v7, vcc
	v_rsq_f32_e32 v6, v6
	s_nop 0
	v_mul_f32_e32 v7, 0x45800000, v6
	v_cndmask_b32_e32 v6, v6, v7, vcc
	ds_write_b32 v69, v6 offset:28
	v_fmamk_f32 v6, v116, 0x3b000000, v208
	v_mul_f32_e32 v7, 0x4b800000, v6
	v_cmp_gt_f32_e32 vcc, s44, v6
	s_nop 1
	v_cndmask_b32_e32 v6, v6, v7, vcc
	v_rsq_f32_e32 v6, v6
	s_nop 0
	v_mul_f32_e32 v7, 0x45800000, v6
	v_cndmask_b32_e32 v6, v6, v7, vcc
	ds_write_b32 v69, v6 offset:32
	v_fmamk_f32 v6, v120, 0x3b000000, v208
	v_mul_f32_e32 v7, 0x4b800000, v6
	v_cmp_gt_f32_e32 vcc, s44, v6
	s_nop 1
	v_cndmask_b32_e32 v6, v6, v7, vcc
	v_rsq_f32_e32 v6, v6
	s_nop 0
	v_mul_f32_e32 v7, 0x45800000, v6
	v_cndmask_b32_e32 v6, v6, v7, vcc
	ds_write_b32 v69, v6 offset:36
	v_fmamk_f32 v6, v124, 0x3b000000, v208
	v_mul_f32_e32 v7, 0x4b800000, v6
	v_cmp_gt_f32_e32 vcc, s44, v6
	s_nop 1
	v_cndmask_b32_e32 v6, v6, v7, vcc
	v_rsq_f32_e32 v6, v6
	s_nop 0
	v_mul_f32_e32 v7, 0x45800000, v6
	v_cndmask_b32_e32 v6, v6, v7, vcc
	ds_write_b32 v69, v6 offset:40
	v_fmamk_f32 v6, v128, 0x3b000000, v208
	v_mul_f32_e32 v7, 0x4b800000, v6
	v_cmp_gt_f32_e32 vcc, s44, v6
	s_nop 1
	v_cndmask_b32_e32 v6, v6, v7, vcc
	v_rsq_f32_e32 v6, v6
	s_nop 0
	v_mul_f32_e32 v7, 0x45800000, v6
	v_cndmask_b32_e32 v6, v6, v7, vcc
	ds_write_b32 v69, v6 offset:44
	v_fmamk_f32 v6, v132, 0x3b000000, v208
	v_mul_f32_e32 v7, 0x4b800000, v6
	v_cmp_gt_f32_e32 vcc, s44, v6
	s_nop 1
	v_cndmask_b32_e32 v6, v6, v7, vcc
	v_rsq_f32_e32 v6, v6
	s_nop 0
	v_mul_f32_e32 v7, 0x45800000, v6
	v_cndmask_b32_e32 v6, v6, v7, vcc
	ds_write_b32 v69, v6 offset:48
	v_fmamk_f32 v6, v136, 0x3b000000, v208
	v_mul_f32_e32 v7, 0x4b800000, v6
	v_cmp_gt_f32_e32 vcc, s44, v6
	s_nop 1
	v_cndmask_b32_e32 v6, v6, v7, vcc
	v_rsq_f32_e32 v6, v6
	s_nop 0
	v_mul_f32_e32 v7, 0x45800000, v6
	v_cndmask_b32_e32 v6, v6, v7, vcc
	ds_write_b32 v69, v6 offset:52
	v_fmamk_f32 v6, v140, 0x3b000000, v208
	v_mul_f32_e32 v7, 0x4b800000, v6
	v_cmp_gt_f32_e32 vcc, s44, v6
	s_nop 1
	v_cndmask_b32_e32 v6, v6, v7, vcc
	v_rsq_f32_e32 v6, v6
	s_nop 0
	v_mul_f32_e32 v7, 0x45800000, v6
	v_cndmask_b32_e32 v6, v6, v7, vcc
	ds_write_b32 v69, v6 offset:56
	v_fmamk_f32 v6, v144, 0x3b000000, v208
	v_mul_f32_e32 v7, 0x4b800000, v6
	v_cmp_gt_f32_e32 vcc, s44, v6
	s_nop 1
	v_cndmask_b32_e32 v6, v6, v7, vcc
	v_rsq_f32_e32 v6, v6
	s_nop 0
	v_mul_f32_e32 v7, 0x45800000, v6
	v_cndmask_b32_e32 v6, v6, v7, vcc
	ds_write_b32 v70, v6
	s_or_b64 exec, exec, s[16:17]
	s_waitcnt lgkmcnt(0)
	s_barrier
	s_load_dwordx2 s[4:5], s[0:1], 0x90
	s_waitcnt lgkmcnt(0)
	v_lshl_add_u64 v[0:1], s[4:5], 0, v[50:51]
	v_lshl_add_u64 v[52:53], v[0:1], 0, 16
	s_mov_b64 s[4:5], 0
